# v119 + epilogue de-serialisation: counted vmcnt waits in the QKV-projection epilogue and parallel gate loads in the FFN2 down-projection epilogue (hot-loop placement unchanged)
# speedup vs baseline: 1.0044x; 1.0044x over previous
;     __device__ __forceinline__ void operator()(const f32x4 (&acc)[2][2][4][2], const Unit& u, int wr, int wc, int fr, int fq) const {
;     ...
;                 if (rope) {
; #pragma unroll
;                     for (int n = 0; n < 2; ++n) { const f32x4 c = cs[m][n], s = sn[m][n];
;                         const f32x4 a = x[0][n], b = x[1][n]; x[0][n] = a * c - b * s; x[1][n] = b * c + a * s; }
;                 }
.LBB0_413:
	s_waitcnt vmcnt(4)
	v_pk_mul_f32 v[198:199], v[168:169], v[160:161]
	v_pk_mul_f32 v[194:195], v[170:171], v[162:163]
	v_pk_fma_f32 v[198:199], v[152:153], v[172:173], v[198:199] neg_lo:[0,0,1] neg_hi:[0,0,1]
	v_pk_mul_f32 v[172:173], v[168:169], v[172:173]
	v_pk_fma_f32 v[200:201], v[154:155], v[174:175], v[194:195] neg_lo:[0,0,1] neg_hi:[0,0,1]
	v_pk_mul_f32 v[174:175], v[170:171], v[174:175]
	v_pk_fma_f32 v[160:161], v[152:153], v[160:161], v[172:173]
	v_pk_mul_f32 v[172:173], v[158:159], v[150:151]
	v_pk_mul_f32 v[194:195], v[156:157], v[148:149]
	v_pk_fma_f32 v[162:163], v[154:155], v[162:163], v[174:175]
	v_pk_fma_f32 v[174:175], v[146:147], v[166:167], v[172:173] neg_lo:[0,0,1] neg_hi:[0,0,1]
	v_pk_fma_f32 v[172:173], v[144:145], v[164:165], v[194:195] neg_lo:[0,0,1] neg_hi:[0,0,1]
	v_pk_mul_f32 v[166:167], v[158:159], v[166:167]
	v_pk_mul_f32 v[164:165], v[156:157], v[164:165]
	v_pk_fma_f32 v[150:151], v[146:147], v[150:151], v[166:167]
	v_pk_fma_f32 v[148:149], v[144:145], v[148:149], v[164:165]
	v_mov_b64_e32 v[164:165], v[172:173]
	v_mov_b64_e32 v[166:167], v[174:175]
	v_mov_b64_e32 v[172:173], v[198:199]
	v_mov_b64_e32 v[174:175], v[200:201]

;     __device__ __forceinline__ void operator()(const f32x4 (&acc)[2][2][4][2], const Unit& u, int wr, int wc, int fr, int fq) const {
;     ...
;                 if (rope) {
; #pragma unroll
;                     for (int n = 0; n < 2; ++n) { const f32x4 c = cs[m][n], s = sn[m][n];
;                         const f32x4 a = x[0][n], b = x[1][n]; x[0][n] = a * c - b * s; x[1][n] = b * c + a * s; }
;                 }
.LBB0_421:
	s_waitcnt vmcnt(2)
	v_pk_mul_f32 v[148:149], v[138:139], v[130:131]
	v_pk_mul_f32 v[160:161], v[136:137], v[128:129]
	v_pk_fma_f32 v[150:151], v[122:123], v[142:143], v[148:149] neg_lo:[0,0,1] neg_hi:[0,0,1]
	v_pk_fma_f32 v[148:149], v[120:121], v[140:141], v[160:161] neg_lo:[0,0,1] neg_hi:[0,0,1]
	v_pk_mul_f32 v[140:141], v[136:137], v[140:141]
	v_pk_mul_f32 v[142:143], v[138:139], v[142:143]
	v_pk_fma_f32 v[128:129], v[120:121], v[128:129], v[140:141]
	v_pk_mul_f32 v[140:141], v[126:127], v[118:119]
	v_pk_mul_f32 v[160:161], v[124:125], v[116:117]
	v_pk_fma_f32 v[130:131], v[122:123], v[130:131], v[142:143]
	v_pk_fma_f32 v[142:143], v[110:111], v[134:135], v[140:141] neg_lo:[0,0,1] neg_hi:[0,0,1]
	v_pk_fma_f32 v[140:141], v[108:109], v[132:133], v[160:161] neg_lo:[0,0,1] neg_hi:[0,0,1]
	v_pk_mul_f32 v[134:135], v[126:127], v[134:135]
	v_pk_mul_f32 v[132:133], v[124:125], v[132:133]
	v_pk_fma_f32 v[118:119], v[110:111], v[118:119], v[134:135]
	v_pk_fma_f32 v[116:117], v[108:109], v[116:117], v[132:133]
	v_mov_b64_e32 v[132:133], v[140:141]
	v_mov_b64_e32 v[134:135], v[142:143]
	v_mov_b64_e32 v[140:141], v[148:149]
	v_mov_b64_e32 v[142:143], v[150:151]

;     __device__ __forceinline__ void operator()(const f32x4 (&acc)[2][2][4][2], const Unit& u, int wr, int wc, int fr, int fq) const {
;     ...
;                 if (qnorm || knorm) {
;                     float ss = 0.f;
; #pragma unroll
;                     for (int bj = 0; bj < 2; ++bj)
; #pragma unroll
;                         for (int n = 0; n < 2; ++n) ss += (x[bj][n][0] * x[bj][n][0] + x[bj][n][1] * x[bj][n][1]) + (x[bj][n][2] * x[bj][n][2] + x[bj][n][3] * x[bj][n][3]);
;                     ss += __shfl_xor(ss, 16); ss += __shfl_xor(ss, 32);
;                     const float rs = __builtin_amdgcn_rsqf(ss * (1.0f / 64.0f) + 1e-6f);
; #pragma unroll
;                     for (int bj = 0; bj < 2; ++bj)
; #pragma unroll
;                         for (int n = 0; n < 2; ++n) x[bj][n] = x[bj][n] * rs * gn[bj][n];
;                 }
.LBB0_426:
	v_pk_mul_f32 v[148:149], v[142:143], v[142:143]
	v_pk_mul_f32 v[150:151], v[140:141], v[140:141]
	v_cmp_lt_i32_e32 vcc, v254, v203
	v_pk_mov_b32 v[160:161], v[150:151], v[148:149] op_sel:[1,0]
	v_mov_b32_e32 v151, v149
	v_pk_add_f32 v[148:149], v[160:161], v[150:151]
	v_pk_mul_f32 v[150:151], v[134:135], v[134:135]
	v_pk_add_f32 v[148:149], v[148:149], v[148:149] op_sel_hi:[0,1]
	v_pk_mul_f32 v[160:161], v[132:133], v[132:133]
	v_mul_f32_e32 v148, v128, v128
	v_pk_mov_b32 v[162:163], v[160:161], v[150:151] op_sel:[1,0]
	v_mov_b32_e32 v161, v151
	v_pk_add_f32 v[150:151], v[162:163], v[160:161]
	v_pk_fma_f32 v[160:161], v[128:129], v[128:129], v[148:149] op_sel_hi:[1,1,0]
	v_mul_f32_e32 v148, v130, v130
	v_pk_add_f32 v[150:151], v[150:151], v[150:151] op_sel_hi:[0,1]
	v_pk_fma_f32 v[162:163], v[130:131], v[130:131], v[148:149] op_sel_hi:[1,1,0]
	v_mul_f32_e32 v160, v116, v116
	v_mul_f32_e32 v162, v117, v117
	v_mul_f32_e32 v150, v118, v118
	v_mul_f32_e32 v148, v119, v119
	v_pk_add_f32 v[160:161], v[160:161], v[162:163]
	v_pk_add_f32 v[148:149], v[150:151], v[148:149]
	s_nop 0
	v_pk_add_f32 v[148:149], v[160:161], v[148:149]
	s_nop 0
	v_add_f32_e32 v148, v148, v149
	v_cndmask_b32_e32 v149, v193, v254, vcc
	v_lshlrev_b32_e32 v149, 2, v149
	ds_bpermute_b32 v149, v149, v148
	v_cmp_lt_i32_e32 vcc, v214, v203
	s_waitcnt lgkmcnt(0)
	v_add_f32_e32 v148, v148, v149
	v_cndmask_b32_e32 v149, v193, v214, vcc
	v_lshlrev_b32_e32 v149, 2, v149
	ds_bpermute_b32 v149, v149, v148
	s_waitcnt lgkmcnt(0)
	v_add_f32_e32 v148, v148, v149
	v_fmamk_f32 v148, v148, 0x3c800000, v207
	v_rsq_f32_e32 v148, v148
	s_nop 0
	v_pk_mul_f32 v[140:141], v[140:141], v[148:149] op_sel_hi:[1,0]
	v_pk_mul_f32 v[142:143], v[142:143], v[148:149] op_sel_hi:[1,0]
	v_pk_mul_f32 v[132:133], v[132:133], v[148:149] op_sel_hi:[1,0]
	v_pk_mul_f32 v[134:135], v[134:135], v[148:149] op_sel_hi:[1,0]
	v_pk_mul_f32 v[128:129], v[128:129], v[148:149] op_sel_hi:[1,0]
	v_pk_mul_f32 v[130:131], v[130:131], v[148:149] op_sel_hi:[1,0]
	v_pk_mul_f32 v[116:117], v[116:117], v[148:149] op_sel_hi:[1,0]
	v_pk_mul_f32 v[118:119], v[118:119], v[148:149] op_sel_hi:[1,0]
	s_waitcnt vmcnt(2)
	v_pk_mul_f32 v[142:143], v[74:75], v[142:143]
	v_pk_mul_f32 v[140:141], v[72:73], v[140:141]
	v_pk_mul_f32 v[134:135], v[70:71], v[134:135]
	v_pk_mul_f32 v[132:133], v[68:69], v[132:133]
	v_pk_mul_f32 v[130:131], v[66:67], v[130:131]
	v_pk_mul_f32 v[128:129], v[64:65], v[128:129]
	v_pk_mul_f32 v[118:119], v[58:59], v[118:119]
	v_pk_mul_f32 v[116:117], v[56:57], v[116:117]
	s_and_b64 vcc, exec, s[4:5]
	s_cbranch_vccz .LBB0_421
	s_branch .LBB0_422

;     __device__ __forceinline__ void operator()(const f32x4 (&acc)[2][2][4][2], const Unit& u, int wr, int wc, int fr, int fq) const {
;     ...
;                 if (rope) {
; #pragma unroll
;                     for (int n = 0; n < 2; ++n) { const f32x4 c = cs[m][n], s = sn[m][n];
;                         const f32x4 a = x[0][n], b = x[1][n]; x[0][n] = a * c - b * s; x[1][n] = b * c + a * s; }
;                 }
.LBB0_431:
	s_waitcnt vmcnt(4)
	v_pk_mul_f32 v[204:205], v[172:173], v[100:101]
	v_pk_mul_f32 v[194:195], v[174:175], v[102:103]
	v_pk_fma_f32 v[210:211], v[160:161], v[112:113], v[204:205] neg_lo:[0,0,1] neg_hi:[0,0,1]
	v_pk_mul_f32 v[112:113], v[172:173], v[112:113]
	v_pk_fma_f32 v[212:213], v[162:163], v[114:115], v[194:195] neg_lo:[0,0,1] neg_hi:[0,0,1]
	v_pk_mul_f32 v[114:115], v[174:175], v[114:115]
	v_pk_fma_f32 v[100:101], v[160:161], v[100:101], v[112:113]
	v_pk_mul_f32 v[112:113], v[166:167], v[98:99]
	v_pk_mul_f32 v[194:195], v[164:165], v[96:97]
	v_pk_fma_f32 v[102:103], v[162:163], v[102:103], v[114:115]
	v_pk_fma_f32 v[114:115], v[150:151], v[106:107], v[112:113] neg_lo:[0,0,1] neg_hi:[0,0,1]
	v_pk_fma_f32 v[112:113], v[148:149], v[104:105], v[194:195] neg_lo:[0,0,1] neg_hi:[0,0,1]
	v_pk_mul_f32 v[106:107], v[166:167], v[106:107]
	v_pk_mul_f32 v[104:105], v[164:165], v[104:105]
	v_pk_fma_f32 v[98:99], v[150:151], v[98:99], v[106:107]
	v_pk_fma_f32 v[96:97], v[148:149], v[96:97], v[104:105]
	v_mov_b64_e32 v[104:105], v[112:113]
	v_mov_b64_e32 v[106:107], v[114:115]
	v_mov_b64_e32 v[112:113], v[210:211]
	v_mov_b64_e32 v[114:115], v[212:213]

;     __device__ __forceinline__ void operator()(const f32x4 (&acc)[2][2][4][2], const Unit& u, int wr, int wc, int fr, int fq) const {
;     ...
;                 if (qnorm || knorm) {
;                     float ss = 0.f;
; #pragma unroll
;                     for (int bj = 0; bj < 2; ++bj)
; #pragma unroll
;                         for (int n = 0; n < 2; ++n) ss += (x[bj][n][0] * x[bj][n][0] + x[bj][n][1] * x[bj][n][1]) + (x[bj][n][2] * x[bj][n][2] + x[bj][n][3] * x[bj][n][3]);
;                     ss += __shfl_xor(ss, 16); ss += __shfl_xor(ss, 32);
;                     const float rs = __builtin_amdgcn_rsqf(ss * (1.0f / 64.0f) + 1e-6f);
; #pragma unroll
;                     for (int bj = 0; bj < 2; ++bj)
; #pragma unroll
;                         for (int n = 0; n < 2; ++n) x[bj][n] = x[bj][n] * rs * gn[bj][n];
;                 }
.LBB0_434:
	v_pk_mul_f32 v[194:195], v[114:115], v[114:115]
	v_pk_mul_f32 v[204:205], v[112:113], v[112:113]
	v_cmp_lt_i32_e32 vcc, v254, v203
	v_pk_mov_b32 v[208:209], v[204:205], v[194:195] op_sel:[1,0]
	v_mov_b32_e32 v205, v195
	v_pk_add_f32 v[194:195], v[208:209], v[204:205]
	v_pk_mul_f32 v[204:205], v[106:107], v[106:107]
	v_pk_add_f32 v[194:195], v[194:195], v[194:195] op_sel_hi:[0,1]
	v_pk_mul_f32 v[208:209], v[104:105], v[104:105]
	v_mul_f32_e32 v194, v100, v100
	v_pk_mov_b32 v[210:211], v[208:209], v[204:205] op_sel:[1,0]
	v_mov_b32_e32 v209, v205
	v_pk_add_f32 v[204:205], v[210:211], v[208:209]
	v_pk_fma_f32 v[208:209], v[100:101], v[100:101], v[194:195] op_sel_hi:[1,1,0]
	v_mul_f32_e32 v194, v102, v102
	v_pk_add_f32 v[204:205], v[204:205], v[204:205] op_sel_hi:[0,1]
	v_pk_fma_f32 v[210:211], v[102:103], v[102:103], v[194:195] op_sel_hi:[1,1,0]
	v_mul_f32_e32 v208, v96, v96
	v_mul_f32_e32 v210, v97, v97
	v_mul_f32_e32 v204, v98, v98
	v_mul_f32_e32 v194, v99, v99
	v_pk_add_f32 v[208:209], v[208:209], v[210:211]
	v_pk_add_f32 v[194:195], v[204:205], v[194:195]
	s_nop 0
	v_pk_add_f32 v[194:195], v[208:209], v[194:195]
	s_nop 0
	v_add_f32_e32 v194, v194, v195
	v_cndmask_b32_e32 v195, v193, v254, vcc
	v_lshlrev_b32_e32 v195, 2, v195
	ds_bpermute_b32 v195, v195, v194
	v_cmp_lt_i32_e32 vcc, v214, v203
	s_waitcnt lgkmcnt(0)
	v_add_f32_e32 v194, v194, v195
	v_cndmask_b32_e32 v195, v193, v214, vcc
	v_lshlrev_b32_e32 v195, 2, v195
	ds_bpermute_b32 v195, v195, v194
	s_waitcnt lgkmcnt(0)
	v_add_f32_e32 v194, v194, v195
	v_fmamk_f32 v194, v194, 0x3c800000, v207
	v_rsq_f32_e32 v194, v194
	s_nop 0
	v_pk_mul_f32 v[112:113], v[112:113], v[194:195] op_sel_hi:[1,0]
	v_pk_mul_f32 v[114:115], v[114:115], v[194:195] op_sel_hi:[1,0]
	v_pk_mul_f32 v[104:105], v[104:105], v[194:195] op_sel_hi:[1,0]
	v_pk_mul_f32 v[106:107], v[106:107], v[194:195] op_sel_hi:[1,0]
	v_pk_mul_f32 v[100:101], v[100:101], v[194:195] op_sel_hi:[1,0]
	v_pk_mul_f32 v[102:103], v[102:103], v[194:195] op_sel_hi:[1,0]
	v_pk_mul_f32 v[96:97], v[96:97], v[194:195] op_sel_hi:[1,0]
	v_pk_mul_f32 v[98:99], v[98:99], v[194:195] op_sel_hi:[1,0]
	s_waitcnt vmcnt(12)
	v_pk_mul_f32 v[114:115], v[74:75], v[114:115]
	v_pk_mul_f32 v[112:113], v[72:73], v[112:113]
	v_pk_mul_f32 v[106:107], v[70:71], v[106:107]
	v_pk_mul_f32 v[104:105], v[68:69], v[104:105]
	v_pk_mul_f32 v[102:103], v[66:67], v[102:103]
	v_pk_mul_f32 v[100:101], v[64:65], v[100:101]
	v_pk_mul_f32 v[98:99], v[58:59], v[98:99]
	v_pk_mul_f32 v[96:97], v[56:57], v[96:97]
	s_and_b64 vcc, exec, s[4:5]
	s_cbranch_vccz .LBB0_431
	s_branch .LBB0_432

;     __device__ __forceinline__ void operator()(const f32x4 (&acc)[2][2][4][2], const Unit& u, int wr, int wc, int fr, int fq) const {
;     ...
;                 if (rope) {
; #pragma unroll
;                     for (int n = 0; n < 2; ++n) { const f32x4 c = cs[m][n], s = sn[m][n];
;                         const f32x4 a = x[0][n], b = x[1][n]; x[0][n] = a * c - b * s; x[1][n] = b * c + a * s; }
;                 }
.LBB0_439:
	s_waitcnt vmcnt(2)
	v_pk_mul_f32 v[96:97], v[142:143], v[86:87]
	v_pk_mul_f32 v[100:101], v[140:141], v[84:85]
	v_pk_fma_f32 v[98:99], v[130:131], v[94:95], v[96:97] neg_lo:[0,0,1] neg_hi:[0,0,1]
	v_pk_fma_f32 v[96:97], v[128:129], v[92:93], v[100:101] neg_lo:[0,0,1] neg_hi:[0,0,1]
	v_pk_mul_f32 v[92:93], v[140:141], v[92:93]
	v_pk_mul_f32 v[94:95], v[142:143], v[94:95]
	v_pk_fma_f32 v[84:85], v[128:129], v[84:85], v[92:93]
	v_pk_mul_f32 v[92:93], v[134:135], v[82:83]
	v_pk_mul_f32 v[100:101], v[132:133], v[80:81]
	v_pk_fma_f32 v[86:87], v[130:131], v[86:87], v[94:95]
	v_pk_fma_f32 v[94:95], v[118:119], v[90:91], v[92:93] neg_lo:[0,0,1] neg_hi:[0,0,1]
	v_pk_fma_f32 v[92:93], v[116:117], v[88:89], v[100:101] neg_lo:[0,0,1] neg_hi:[0,0,1]
	v_pk_mul_f32 v[90:91], v[134:135], v[90:91]
	v_pk_mul_f32 v[88:89], v[132:133], v[88:89]
	v_pk_fma_f32 v[82:83], v[118:119], v[82:83], v[90:91]
	v_pk_fma_f32 v[80:81], v[116:117], v[80:81], v[88:89]
	v_mov_b64_e32 v[88:89], v[92:93]
	v_mov_b64_e32 v[90:91], v[94:95]
	v_mov_b64_e32 v[92:93], v[96:97]
	v_mov_b64_e32 v[94:95], v[98:99]

;     __device__ __forceinline__ void operator()(const f32x4 (&acc)[2][2][4][2], const Unit& u, int wr, int wc, int fr, int fq) const {
;     ...
;                 if (qnorm || knorm) {
;                     float ss = 0.f;
; #pragma unroll
;                     for (int bj = 0; bj < 2; ++bj)
; #pragma unroll
;                         for (int n = 0; n < 2; ++n) ss += (x[bj][n][0] * x[bj][n][0] + x[bj][n][1] * x[bj][n][1]) + (x[bj][n][2] * x[bj][n][2] + x[bj][n][3] * x[bj][n][3]);
;                     ss += __shfl_xor(ss, 16); ss += __shfl_xor(ss, 32);
;                     const float rs = __builtin_amdgcn_rsqf(ss * (1.0f / 64.0f) + 1e-6f);
; #pragma unroll
;                     for (int bj = 0; bj < 2; ++bj)
; #pragma unroll
;                         for (int n = 0; n < 2; ++n) x[bj][n] = x[bj][n] * rs * gn[bj][n];
;                 }
.LBB0_444:
	v_pk_mul_f32 v[96:97], v[94:95], v[94:95]
	v_pk_mul_f32 v[98:99], v[92:93], v[92:93]
	v_cmp_lt_i32_e32 vcc, v254, v203
	v_pk_mov_b32 v[100:101], v[98:99], v[96:97] op_sel:[1,0]
	v_mov_b32_e32 v99, v97
	v_pk_add_f32 v[96:97], v[100:101], v[98:99]
	v_pk_mul_f32 v[98:99], v[90:91], v[90:91]
	v_pk_add_f32 v[96:97], v[96:97], v[96:97] op_sel_hi:[0,1]
	v_pk_mul_f32 v[100:101], v[88:89], v[88:89]
	v_mul_f32_e32 v96, v84, v84
	v_pk_mov_b32 v[102:103], v[100:101], v[98:99] op_sel:[1,0]
	v_mov_b32_e32 v101, v99
	v_pk_add_f32 v[98:99], v[102:103], v[100:101]
	v_pk_fma_f32 v[100:101], v[84:85], v[84:85], v[96:97] op_sel_hi:[1,1,0]
	v_mul_f32_e32 v96, v86, v86
	v_pk_add_f32 v[98:99], v[98:99], v[98:99] op_sel_hi:[0,1]
	v_pk_fma_f32 v[102:103], v[86:87], v[86:87], v[96:97] op_sel_hi:[1,1,0]
	v_mul_f32_e32 v100, v80, v80
	v_mul_f32_e32 v102, v81, v81
	v_mul_f32_e32 v98, v82, v82
	v_mul_f32_e32 v96, v83, v83
	v_pk_add_f32 v[100:101], v[100:101], v[102:103]
	v_pk_add_f32 v[96:97], v[98:99], v[96:97]
	s_nop 0
	v_pk_add_f32 v[96:97], v[100:101], v[96:97]
	s_nop 0
	v_add_f32_e32 v96, v96, v97
	v_cndmask_b32_e32 v97, v193, v254, vcc
	v_lshlrev_b32_e32 v97, 2, v97
	ds_bpermute_b32 v97, v97, v96
	v_cmp_lt_i32_e32 vcc, v214, v203
	s_waitcnt lgkmcnt(0)
	v_add_f32_e32 v96, v96, v97
	v_cndmask_b32_e32 v97, v193, v214, vcc
	v_lshlrev_b32_e32 v97, 2, v97
	ds_bpermute_b32 v97, v97, v96
	s_waitcnt lgkmcnt(0)
	v_add_f32_e32 v96, v96, v97
	v_fmamk_f32 v96, v96, 0x3c800000, v207
	v_rsq_f32_e32 v96, v96
	s_nop 0
	v_pk_mul_f32 v[92:93], v[92:93], v[96:97] op_sel_hi:[1,0]
	v_pk_mul_f32 v[94:95], v[94:95], v[96:97] op_sel_hi:[1,0]
	v_pk_mul_f32 v[88:89], v[88:89], v[96:97] op_sel_hi:[1,0]
	v_pk_mul_f32 v[90:91], v[90:91], v[96:97] op_sel_hi:[1,0]
	v_pk_mul_f32 v[84:85], v[84:85], v[96:97] op_sel_hi:[1,0]
	v_pk_mul_f32 v[86:87], v[86:87], v[96:97] op_sel_hi:[1,0]
	v_pk_mul_f32 v[80:81], v[80:81], v[96:97] op_sel_hi:[1,0]
	v_pk_mul_f32 v[82:83], v[82:83], v[96:97] op_sel_hi:[1,0]
	s_waitcnt vmcnt(2)
	v_pk_mul_f32 v[94:95], v[74:75], v[94:95]
	v_pk_mul_f32 v[92:93], v[72:73], v[92:93]
	v_pk_mul_f32 v[90:91], v[70:71], v[90:91]
	v_pk_mul_f32 v[88:89], v[68:69], v[88:89]
	v_pk_mul_f32 v[86:87], v[66:67], v[86:87]
	v_pk_mul_f32 v[84:85], v[64:65], v[84:85]
	v_pk_mul_f32 v[82:83], v[58:59], v[82:83]
	v_pk_mul_f32 v[80:81], v[56:57], v[80:81]
	s_and_b64 vcc, exec, s[4:5]
	s_cbranch_vccz .LBB0_439
	s_branch .LBB0_440

;     __device__ __forceinline__ void operator()(const f32x4 (&acc)[2][2][4][2], const Unit& u, int wr, int wc, int fr, int fq) const {
;     ...
;                 if (rope) {
; #pragma unroll
;                     for (int n = 0; n < 2; ++n) { const f32x4 c = cs[m][n], s = sn[m][n];
;                         const f32x4 a = x[0][n], b = x[1][n]; x[0][n] = a * c - b * s; x[1][n] = b * c + a * s; }
;                 }
.LBB0_449:
	s_waitcnt vmcnt(4)
	v_pk_mul_f32 v[80:81], v[170:171], v[54:55]
	v_pk_mul_f32 v[84:85], v[168:169], v[52:53]
	v_pk_fma_f32 v[82:83], v[154:155], v[78:79], v[80:81] neg_lo:[0,0,1] neg_hi:[0,0,1]
	v_pk_fma_f32 v[80:81], v[152:153], v[76:77], v[84:85] neg_lo:[0,0,1] neg_hi:[0,0,1]
	v_pk_mul_f32 v[76:77], v[168:169], v[76:77]
	v_pk_mul_f32 v[78:79], v[170:171], v[78:79]
	v_pk_fma_f32 v[52:53], v[152:153], v[52:53], v[76:77]
	v_pk_mul_f32 v[76:77], v[158:159], v[50:51]
	v_pk_mul_f32 v[84:85], v[156:157], v[48:49]
	v_pk_fma_f32 v[54:55], v[154:155], v[54:55], v[78:79]
	v_pk_fma_f32 v[78:79], v[146:147], v[62:63], v[76:77] neg_lo:[0,0,1] neg_hi:[0,0,1]
	v_pk_fma_f32 v[76:77], v[144:145], v[60:61], v[84:85] neg_lo:[0,0,1] neg_hi:[0,0,1]
	v_pk_mul_f32 v[62:63], v[158:159], v[62:63]
	v_pk_mul_f32 v[60:61], v[156:157], v[60:61]
	v_pk_fma_f32 v[50:51], v[146:147], v[50:51], v[62:63]
	v_pk_fma_f32 v[48:49], v[144:145], v[48:49], v[60:61]
	v_mov_b64_e32 v[60:61], v[76:77]
	v_mov_b64_e32 v[62:63], v[78:79]
	v_mov_b64_e32 v[76:77], v[80:81]
	v_mov_b64_e32 v[78:79], v[82:83]

;     __device__ __forceinline__ void operator()(const f32x4 (&acc)[2][2][4][2], const Unit& u, int wr, int wc, int fr, int fq) const {
;     ...
;                 if (qnorm || knorm) {
;                     float ss = 0.f;
; #pragma unroll
;                     for (int bj = 0; bj < 2; ++bj)
; #pragma unroll
;                         for (int n = 0; n < 2; ++n) ss += (x[bj][n][0] * x[bj][n][0] + x[bj][n][1] * x[bj][n][1]) + (x[bj][n][2] * x[bj][n][2] + x[bj][n][3] * x[bj][n][3]);
;                     ss += __shfl_xor(ss, 16); ss += __shfl_xor(ss, 32);
;                     const float rs = __builtin_amdgcn_rsqf(ss * (1.0f / 64.0f) + 1e-6f);
; #pragma unroll
;                     for (int bj = 0; bj < 2; ++bj)
; #pragma unroll
;                         for (int n = 0; n < 2; ++n) x[bj][n] = x[bj][n] * rs * gn[bj][n];
;                 }
.LBB0_452:
	v_pk_mul_f32 v[80:81], v[78:79], v[78:79]
	v_pk_mul_f32 v[82:83], v[76:77], v[76:77]
	v_cmp_lt_i32_e32 vcc, v254, v203
	v_pk_mov_b32 v[84:85], v[82:83], v[80:81] op_sel:[1,0]
	v_mov_b32_e32 v83, v81
	v_pk_add_f32 v[80:81], v[84:85], v[82:83]
	v_pk_mul_f32 v[82:83], v[62:63], v[62:63]
	v_pk_add_f32 v[80:81], v[80:81], v[80:81] op_sel_hi:[0,1]
	v_pk_mul_f32 v[84:85], v[60:61], v[60:61]
	v_mul_f32_e32 v80, v52, v52
	v_pk_mov_b32 v[86:87], v[84:85], v[82:83] op_sel:[1,0]
	v_mov_b32_e32 v85, v83
	v_pk_add_f32 v[82:83], v[86:87], v[84:85]
	v_pk_fma_f32 v[84:85], v[52:53], v[52:53], v[80:81] op_sel_hi:[1,1,0]
	v_mul_f32_e32 v80, v54, v54
	v_pk_add_f32 v[82:83], v[82:83], v[82:83] op_sel_hi:[0,1]
	v_pk_fma_f32 v[86:87], v[54:55], v[54:55], v[80:81] op_sel_hi:[1,1,0]
	v_mul_f32_e32 v84, v48, v48
	v_mul_f32_e32 v86, v49, v49
	v_mul_f32_e32 v82, v50, v50
	v_mul_f32_e32 v80, v51, v51
	v_pk_add_f32 v[84:85], v[84:85], v[86:87]
	v_pk_add_f32 v[80:81], v[82:83], v[80:81]
	s_nop 0
	v_pk_add_f32 v[80:81], v[84:85], v[80:81]
	s_nop 0
	v_add_f32_e32 v80, v80, v81
	v_cndmask_b32_e32 v81, v193, v254, vcc
	v_lshlrev_b32_e32 v81, 2, v81
	ds_bpermute_b32 v81, v81, v80
	v_cmp_lt_i32_e32 vcc, v214, v203
	s_waitcnt lgkmcnt(0)
	v_add_f32_e32 v80, v80, v81
	v_cndmask_b32_e32 v81, v193, v214, vcc
	v_lshlrev_b32_e32 v81, 2, v81
	ds_bpermute_b32 v81, v81, v80
	s_waitcnt lgkmcnt(0)
	v_add_f32_e32 v80, v80, v81
	v_fmamk_f32 v80, v80, 0x3c800000, v207
	v_rsq_f32_e32 v80, v80
	s_nop 0
	v_pk_mul_f32 v[76:77], v[76:77], v[80:81] op_sel_hi:[1,0]
	v_pk_mul_f32 v[78:79], v[78:79], v[80:81] op_sel_hi:[1,0]
	v_pk_mul_f32 v[60:61], v[60:61], v[80:81] op_sel_hi:[1,0]
	v_pk_mul_f32 v[62:63], v[62:63], v[80:81] op_sel_hi:[1,0]
	v_pk_mul_f32 v[52:53], v[52:53], v[80:81] op_sel_hi:[1,0]
	v_pk_mul_f32 v[54:55], v[54:55], v[80:81] op_sel_hi:[1,0]
	v_pk_mul_f32 v[48:49], v[48:49], v[80:81] op_sel_hi:[1,0]
	v_pk_mul_f32 v[50:51], v[50:51], v[80:81] op_sel_hi:[1,0]
	s_waitcnt vmcnt(12)
	v_pk_mul_f32 v[78:79], v[74:75], v[78:79]
	v_pk_mul_f32 v[76:77], v[72:73], v[76:77]
	v_pk_mul_f32 v[62:63], v[70:71], v[62:63]
	v_pk_mul_f32 v[60:61], v[68:69], v[60:61]
	v_pk_mul_f32 v[54:55], v[66:67], v[54:55]
	v_pk_mul_f32 v[52:53], v[64:65], v[52:53]
	v_pk_mul_f32 v[50:51], v[58:59], v[50:51]
	v_pk_mul_f32 v[48:49], v[56:57], v[48:49]
	s_and_b64 vcc, exec, s[4:5]
	s_cbranch_vccz .LBB0_449
	s_branch .LBB0_450

;     __device__ __forceinline__ void operator()(const f32x4 (&acc)[2][2][4][2], const Unit& u, int wr, int wc, int fr, int fq) const {
;     ...
;                 if (rope) {
; #pragma unroll
;                     for (int n = 0; n < 2; ++n) { const f32x4 c = cs[m][n], s = sn[m][n];
;                         const f32x4 a = x[0][n], b = x[1][n]; x[0][n] = a * c - b * s; x[1][n] = b * c + a * s; }
;                 }
.LBB0_457:
	s_waitcnt vmcnt(2)
	v_pk_mul_f32 v[48:49], v[138:139], v[38:39]
	v_pk_mul_f32 v[52:53], v[136:137], v[36:37]
	v_pk_fma_f32 v[50:51], v[122:123], v[46:47], v[48:49] neg_lo:[0,0,1] neg_hi:[0,0,1]
	v_pk_fma_f32 v[48:49], v[120:121], v[44:45], v[52:53] neg_lo:[0,0,1] neg_hi:[0,0,1]
	v_pk_mul_f32 v[44:45], v[136:137], v[44:45]
	v_pk_mul_f32 v[46:47], v[138:139], v[46:47]
	v_pk_fma_f32 v[36:37], v[120:121], v[36:37], v[44:45]
	v_pk_mul_f32 v[44:45], v[126:127], v[34:35]
	v_pk_mul_f32 v[52:53], v[124:125], v[32:33]
	v_pk_fma_f32 v[38:39], v[122:123], v[38:39], v[46:47]
	v_pk_fma_f32 v[46:47], v[110:111], v[42:43], v[44:45] neg_lo:[0,0,1] neg_hi:[0,0,1]
	v_pk_fma_f32 v[44:45], v[108:109], v[40:41], v[52:53] neg_lo:[0,0,1] neg_hi:[0,0,1]
	v_pk_mul_f32 v[42:43], v[126:127], v[42:43]
	v_pk_mul_f32 v[40:41], v[124:125], v[40:41]
	v_pk_fma_f32 v[34:35], v[110:111], v[34:35], v[42:43]
	v_pk_fma_f32 v[32:33], v[108:109], v[32:33], v[40:41]
	v_mov_b64_e32 v[40:41], v[44:45]
	v_mov_b64_e32 v[42:43], v[46:47]
	v_mov_b64_e32 v[44:45], v[48:49]
	v_mov_b64_e32 v[46:47], v[50:51]

;     __device__ __forceinline__ void operator()(const f32x4 (&acc)[2][2][4][2], const Unit& u, int wr, int wc, int fr, int fq) const {
;     ...
;                 if (qnorm || knorm) {
;                     float ss = 0.f;
; #pragma unroll
;                     for (int bj = 0; bj < 2; ++bj)
; #pragma unroll
;                         for (int n = 0; n < 2; ++n) ss += (x[bj][n][0] * x[bj][n][0] + x[bj][n][1] * x[bj][n][1]) + (x[bj][n][2] * x[bj][n][2] + x[bj][n][3] * x[bj][n][3]);
;                     ss += __shfl_xor(ss, 16); ss += __shfl_xor(ss, 32);
;                     const float rs = __builtin_amdgcn_rsqf(ss * (1.0f / 64.0f) + 1e-6f);
; #pragma unroll
;                     for (int bj = 0; bj < 2; ++bj)
; #pragma unroll
;                         for (int n = 0; n < 2; ++n) x[bj][n] = x[bj][n] * rs * gn[bj][n];
;                 }
.LBB0_462:
	v_pk_mul_f32 v[48:49], v[46:47], v[46:47]
	v_pk_mul_f32 v[50:51], v[44:45], v[44:45]
	v_cmp_lt_i32_e32 vcc, v254, v203
	v_pk_mov_b32 v[52:53], v[50:51], v[48:49] op_sel:[1,0]
	v_mov_b32_e32 v51, v49
	v_pk_add_f32 v[48:49], v[52:53], v[50:51]
	v_pk_mul_f32 v[50:51], v[42:43], v[42:43]
	v_pk_add_f32 v[48:49], v[48:49], v[48:49] op_sel_hi:[0,1]
	v_pk_mul_f32 v[52:53], v[40:41], v[40:41]
	v_mul_f32_e32 v48, v36, v36
	v_pk_mov_b32 v[54:55], v[52:53], v[50:51] op_sel:[1,0]
	v_mov_b32_e32 v53, v51
	v_pk_add_f32 v[50:51], v[54:55], v[52:53]
	v_pk_fma_f32 v[52:53], v[36:37], v[36:37], v[48:49] op_sel_hi:[1,1,0]
	v_mul_f32_e32 v48, v38, v38
	v_pk_add_f32 v[50:51], v[50:51], v[50:51] op_sel_hi:[0,1]
	v_pk_fma_f32 v[54:55], v[38:39], v[38:39], v[48:49] op_sel_hi:[1,1,0]
	v_mul_f32_e32 v52, v32, v32
	v_mul_f32_e32 v54, v33, v33
	v_mul_f32_e32 v50, v34, v34
	v_mul_f32_e32 v48, v35, v35
	v_pk_add_f32 v[52:53], v[52:53], v[54:55]
	v_pk_add_f32 v[48:49], v[50:51], v[48:49]
	s_nop 0
	v_pk_add_f32 v[48:49], v[52:53], v[48:49]
	s_nop 0
	v_add_f32_e32 v48, v48, v49
	v_cndmask_b32_e32 v49, v193, v254, vcc
	v_lshlrev_b32_e32 v49, 2, v49
	ds_bpermute_b32 v49, v49, v48
	v_cmp_lt_i32_e32 vcc, v214, v203
	s_waitcnt lgkmcnt(0)
	v_add_f32_e32 v48, v48, v49
	v_cndmask_b32_e32 v49, v193, v214, vcc
	v_lshlrev_b32_e32 v49, 2, v49
	ds_bpermute_b32 v49, v49, v48
	s_waitcnt lgkmcnt(0)
	v_add_f32_e32 v48, v48, v49
	v_fmamk_f32 v48, v48, 0x3c800000, v207
	v_rsq_f32_e32 v48, v48
	s_nop 0
	v_pk_mul_f32 v[44:45], v[44:45], v[48:49] op_sel_hi:[1,0]
	v_pk_mul_f32 v[46:47], v[46:47], v[48:49] op_sel_hi:[1,0]
	v_pk_mul_f32 v[40:41], v[40:41], v[48:49] op_sel_hi:[1,0]
	v_pk_mul_f32 v[42:43], v[42:43], v[48:49] op_sel_hi:[1,0]
	v_pk_mul_f32 v[36:37], v[36:37], v[48:49] op_sel_hi:[1,0]
	v_pk_mul_f32 v[38:39], v[38:39], v[48:49] op_sel_hi:[1,0]
	v_pk_mul_f32 v[32:33], v[32:33], v[48:49] op_sel_hi:[1,0]
	v_pk_mul_f32 v[34:35], v[34:35], v[48:49] op_sel_hi:[1,0]
	s_waitcnt vmcnt(2)
	v_pk_mul_f32 v[46:47], v[74:75], v[46:47]
	v_pk_mul_f32 v[44:45], v[72:73], v[44:45]
	v_pk_mul_f32 v[42:43], v[70:71], v[42:43]
	v_pk_mul_f32 v[40:41], v[68:69], v[40:41]
	v_pk_mul_f32 v[38:39], v[66:67], v[38:39]
	v_pk_mul_f32 v[36:37], v[64:65], v[36:37]
	v_pk_mul_f32 v[34:35], v[58:59], v[34:35]
	v_pk_mul_f32 v[32:33], v[56:57], v[32:33]
	s_and_b64 vcc, exec, s[4:5]
	s_cbranch_vccz .LBB0_457
	s_branch .LBB0_458

;     __device__ __forceinline__ void operator()(const f32x4 (&acc)[2][2][4][2], const Unit& u, int wr, int wc, int fr, int fq) const {
;     ...
;                 if (rope) {
; #pragma unroll
;                     for (int n = 0; n < 2; ++n) { const f32x4 c = cs[m][n], s = sn[m][n];
;                         const f32x4 a = x[0][n], b = x[1][n]; x[0][n] = a * c - b * s; x[1][n] = b * c + a * s; }
;                 }
.LBB0_467:
	s_waitcnt vmcnt(4)
	v_pk_mul_f32 v[32:33], v[174:175], v[22:23]
	v_pk_mul_f32 v[36:37], v[172:173], v[20:21]
	v_pk_fma_f32 v[34:35], v[162:163], v[30:31], v[32:33] neg_lo:[0,0,1] neg_hi:[0,0,1]
	v_pk_fma_f32 v[32:33], v[160:161], v[28:29], v[36:37] neg_lo:[0,0,1] neg_hi:[0,0,1]
	v_pk_mul_f32 v[28:29], v[172:173], v[28:29]
	v_pk_mul_f32 v[30:31], v[174:175], v[30:31]
	v_pk_fma_f32 v[20:21], v[160:161], v[20:21], v[28:29]
	v_pk_mul_f32 v[28:29], v[166:167], v[18:19]
	v_pk_mul_f32 v[36:37], v[164:165], v[16:17]
	v_pk_fma_f32 v[22:23], v[162:163], v[22:23], v[30:31]
	v_pk_fma_f32 v[30:31], v[150:151], v[26:27], v[28:29] neg_lo:[0,0,1] neg_hi:[0,0,1]
	v_pk_fma_f32 v[28:29], v[148:149], v[24:25], v[36:37] neg_lo:[0,0,1] neg_hi:[0,0,1]
	v_pk_mul_f32 v[26:27], v[166:167], v[26:27]
	v_pk_mul_f32 v[24:25], v[164:165], v[24:25]
	v_pk_fma_f32 v[18:19], v[150:151], v[18:19], v[26:27]
	v_pk_fma_f32 v[16:17], v[148:149], v[16:17], v[24:25]
	v_mov_b64_e32 v[24:25], v[28:29]
	v_mov_b64_e32 v[26:27], v[30:31]
	v_mov_b64_e32 v[28:29], v[32:33]
	v_mov_b64_e32 v[30:31], v[34:35]

;     __device__ __forceinline__ void operator()(const f32x4 (&acc)[2][2][4][2], const Unit& u, int wr, int wc, int fr, int fq) const {
;     ...
;                 if (qnorm || knorm) {
;                     float ss = 0.f;
; #pragma unroll
;                     for (int bj = 0; bj < 2; ++bj)
; #pragma unroll
;                         for (int n = 0; n < 2; ++n) ss += (x[bj][n][0] * x[bj][n][0] + x[bj][n][1] * x[bj][n][1]) + (x[bj][n][2] * x[bj][n][2] + x[bj][n][3] * x[bj][n][3]);
;                     ss += __shfl_xor(ss, 16); ss += __shfl_xor(ss, 32);
;                     const float rs = __builtin_amdgcn_rsqf(ss * (1.0f / 64.0f) + 1e-6f);
; #pragma unroll
;                     for (int bj = 0; bj < 2; ++bj)
; #pragma unroll
;                         for (int n = 0; n < 2; ++n) x[bj][n] = x[bj][n] * rs * gn[bj][n];
;                 }
.LBB0_470:
	v_pk_mul_f32 v[32:33], v[30:31], v[30:31]
	v_pk_mul_f32 v[34:35], v[28:29], v[28:29]
	v_cmp_lt_i32_e32 vcc, v254, v203
	v_pk_mov_b32 v[36:37], v[34:35], v[32:33] op_sel:[1,0]
	v_mov_b32_e32 v35, v33
	v_pk_add_f32 v[32:33], v[36:37], v[34:35]
	v_pk_mul_f32 v[34:35], v[26:27], v[26:27]
	v_pk_add_f32 v[32:33], v[32:33], v[32:33] op_sel_hi:[0,1]
	v_pk_mul_f32 v[36:37], v[24:25], v[24:25]
	v_mul_f32_e32 v32, v20, v20
	v_pk_mov_b32 v[38:39], v[36:37], v[34:35] op_sel:[1,0]
	v_mov_b32_e32 v37, v35
	v_pk_add_f32 v[34:35], v[38:39], v[36:37]
	v_pk_fma_f32 v[36:37], v[20:21], v[20:21], v[32:33] op_sel_hi:[1,1,0]
	v_mul_f32_e32 v32, v22, v22
	v_pk_add_f32 v[34:35], v[34:35], v[34:35] op_sel_hi:[0,1]
	v_pk_fma_f32 v[38:39], v[22:23], v[22:23], v[32:33] op_sel_hi:[1,1,0]
	v_mul_f32_e32 v36, v16, v16
	v_mul_f32_e32 v38, v17, v17
	v_mul_f32_e32 v34, v18, v18
	v_mul_f32_e32 v32, v19, v19
	v_pk_add_f32 v[36:37], v[36:37], v[38:39]
	v_pk_add_f32 v[32:33], v[34:35], v[32:33]
	s_nop 0
	v_pk_add_f32 v[32:33], v[36:37], v[32:33]
	s_nop 0
	v_add_f32_e32 v32, v32, v33
	v_cndmask_b32_e32 v33, v193, v254, vcc
	v_lshlrev_b32_e32 v33, 2, v33
	ds_bpermute_b32 v33, v33, v32
	v_cmp_lt_i32_e32 vcc, v214, v203
	s_waitcnt lgkmcnt(0)
	v_add_f32_e32 v32, v32, v33
	v_cndmask_b32_e32 v33, v193, v214, vcc
	v_lshlrev_b32_e32 v33, 2, v33
	ds_bpermute_b32 v33, v33, v32
	s_waitcnt lgkmcnt(0)
	v_add_f32_e32 v32, v32, v33
	v_fmamk_f32 v32, v32, 0x3c800000, v207
	v_rsq_f32_e32 v32, v32
	s_nop 0
	v_pk_mul_f32 v[28:29], v[28:29], v[32:33] op_sel_hi:[1,0]
	v_pk_mul_f32 v[30:31], v[30:31], v[32:33] op_sel_hi:[1,0]
	v_pk_mul_f32 v[24:25], v[24:25], v[32:33] op_sel_hi:[1,0]
	v_pk_mul_f32 v[26:27], v[26:27], v[32:33] op_sel_hi:[1,0]
	v_pk_mul_f32 v[20:21], v[20:21], v[32:33] op_sel_hi:[1,0]
	v_pk_mul_f32 v[22:23], v[22:23], v[32:33] op_sel_hi:[1,0]
	v_pk_mul_f32 v[16:17], v[16:17], v[32:33] op_sel_hi:[1,0]
	v_pk_mul_f32 v[18:19], v[18:19], v[32:33] op_sel_hi:[1,0]
	s_waitcnt vmcnt(12)
	v_pk_mul_f32 v[30:31], v[74:75], v[30:31]
	v_pk_mul_f32 v[28:29], v[72:73], v[28:29]
	v_pk_mul_f32 v[26:27], v[70:71], v[26:27]
	v_pk_mul_f32 v[24:25], v[68:69], v[24:25]
	v_pk_mul_f32 v[22:23], v[66:67], v[22:23]
	v_pk_mul_f32 v[20:21], v[64:65], v[20:21]
	v_pk_mul_f32 v[18:19], v[58:59], v[18:19]
	v_pk_mul_f32 v[16:17], v[56:57], v[16:17]
	s_and_b64 vcc, exec, s[4:5]
	s_cbranch_vccz .LBB0_467
	s_branch .LBB0_468

;     __device__ __forceinline__ void operator()(const f32x4 (&acc)[2][2][4][2], const Unit& u, int wr, int wc, int fr, int fq) const {
;     ...
;                 if (rope) {
; #pragma unroll
;                     for (int n = 0; n < 2; ++n) { const f32x4 c = cs[m][n], s = sn[m][n];
;                         const f32x4 a = x[0][n], b = x[1][n]; x[0][n] = a * c - b * s; x[1][n] = b * c + a * s; }
;                 }
.LBB0_475:
	s_waitcnt vmcnt(2)
	v_pk_mul_f32 v[16:17], v[142:143], v[6:7]
	v_pk_mul_f32 v[20:21], v[140:141], v[4:5]
	v_pk_fma_f32 v[18:19], v[130:131], v[14:15], v[16:17] neg_lo:[0,0,1] neg_hi:[0,0,1]
	v_pk_fma_f32 v[16:17], v[128:129], v[12:13], v[20:21] neg_lo:[0,0,1] neg_hi:[0,0,1]
	v_pk_mul_f32 v[12:13], v[140:141], v[12:13]
	v_pk_mul_f32 v[14:15], v[142:143], v[14:15]
	v_pk_fma_f32 v[4:5], v[128:129], v[4:5], v[12:13]
	v_pk_mul_f32 v[12:13], v[134:135], v[2:3]
	v_pk_mul_f32 v[20:21], v[132:133], v[0:1]
	v_pk_fma_f32 v[6:7], v[130:131], v[6:7], v[14:15]
	v_pk_fma_f32 v[14:15], v[118:119], v[10:11], v[12:13] neg_lo:[0,0,1] neg_hi:[0,0,1]
	v_pk_fma_f32 v[12:13], v[116:117], v[8:9], v[20:21] neg_lo:[0,0,1] neg_hi:[0,0,1]
	v_pk_mul_f32 v[10:11], v[134:135], v[10:11]
	v_pk_mul_f32 v[8:9], v[132:133], v[8:9]
	v_pk_fma_f32 v[2:3], v[118:119], v[2:3], v[10:11]
	v_pk_fma_f32 v[0:1], v[116:117], v[0:1], v[8:9]
	v_mov_b64_e32 v[8:9], v[12:13]
	v_mov_b64_e32 v[10:11], v[14:15]
	v_mov_b64_e32 v[12:13], v[16:17]
	v_mov_b64_e32 v[14:15], v[18:19]

;     __device__ __forceinline__ void operator()(const f32x4 (&acc)[2][2][4][2], const Unit& u, int wr, int wc, int fr, int fq) const {
;     ...
;                 if (qnorm || knorm) {
;                     float ss = 0.f;
; #pragma unroll
;                     for (int bj = 0; bj < 2; ++bj)
; #pragma unroll
;                         for (int n = 0; n < 2; ++n) ss += (x[bj][n][0] * x[bj][n][0] + x[bj][n][1] * x[bj][n][1]) + (x[bj][n][2] * x[bj][n][2] + x[bj][n][3] * x[bj][n][3]);
;                     ss += __shfl_xor(ss, 16); ss += __shfl_xor(ss, 32);
;                     const float rs = __builtin_amdgcn_rsqf(ss * (1.0f / 64.0f) + 1e-6f);
; #pragma unroll
;                     for (int bj = 0; bj < 2; ++bj)
; #pragma unroll
;                         for (int n = 0; n < 2; ++n) x[bj][n] = x[bj][n] * rs * gn[bj][n];
;                 }
.LBB0_479:
	v_pk_mul_f32 v[16:17], v[14:15], v[14:15]
	v_pk_mul_f32 v[18:19], v[12:13], v[12:13]
	v_cmp_lt_i32_e32 vcc, v254, v203
	v_pk_mov_b32 v[20:21], v[18:19], v[16:17] op_sel:[1,0]
	v_mov_b32_e32 v19, v17
	v_pk_add_f32 v[16:17], v[20:21], v[18:19]
	v_pk_mul_f32 v[18:19], v[10:11], v[10:11]
	v_pk_add_f32 v[16:17], v[16:17], v[16:17] op_sel_hi:[0,1]
	v_pk_mul_f32 v[20:21], v[8:9], v[8:9]
	v_mul_f32_e32 v16, v4, v4
	v_pk_mov_b32 v[22:23], v[20:21], v[18:19] op_sel:[1,0]
	v_mov_b32_e32 v21, v19
	v_pk_add_f32 v[18:19], v[22:23], v[20:21]
	v_pk_fma_f32 v[20:21], v[4:5], v[4:5], v[16:17] op_sel_hi:[1,1,0]
	v_mul_f32_e32 v16, v6, v6
	v_pk_add_f32 v[18:19], v[18:19], v[18:19] op_sel_hi:[0,1]
	v_pk_fma_f32 v[22:23], v[6:7], v[6:7], v[16:17] op_sel_hi:[1,1,0]
	v_mul_f32_e32 v20, v0, v0
	v_mul_f32_e32 v22, v1, v1
	v_mul_f32_e32 v18, v2, v2
	v_mul_f32_e32 v16, v3, v3
	v_pk_add_f32 v[20:21], v[20:21], v[22:23]
	v_pk_add_f32 v[16:17], v[18:19], v[16:17]
	s_nop 0
	v_pk_add_f32 v[16:17], v[20:21], v[16:17]
	s_nop 0
	v_add_f32_e32 v16, v16, v17
	v_cndmask_b32_e32 v17, v193, v254, vcc
	v_lshlrev_b32_e32 v17, 2, v17
	ds_bpermute_b32 v17, v17, v16
	v_cmp_lt_i32_e32 vcc, v214, v203
	s_waitcnt lgkmcnt(0)
	v_add_f32_e32 v16, v16, v17
	v_cndmask_b32_e32 v17, v193, v214, vcc
	v_lshlrev_b32_e32 v17, 2, v17
	ds_bpermute_b32 v17, v17, v16
	s_waitcnt lgkmcnt(0)
	v_add_f32_e32 v16, v16, v17
	v_fmamk_f32 v16, v16, 0x3c800000, v207
	v_rsq_f32_e32 v16, v16
	s_nop 0
	v_pk_mul_f32 v[12:13], v[12:13], v[16:17] op_sel_hi:[1,0]
	v_pk_mul_f32 v[14:15], v[14:15], v[16:17] op_sel_hi:[1,0]
	v_pk_mul_f32 v[8:9], v[8:9], v[16:17] op_sel_hi:[1,0]
	v_pk_mul_f32 v[10:11], v[10:11], v[16:17] op_sel_hi:[1,0]
	v_pk_mul_f32 v[4:5], v[4:5], v[16:17] op_sel_hi:[1,0]
	v_pk_mul_f32 v[6:7], v[6:7], v[16:17] op_sel_hi:[1,0]
	v_pk_mul_f32 v[0:1], v[0:1], v[16:17] op_sel_hi:[1,0]
	v_pk_mul_f32 v[2:3], v[2:3], v[16:17] op_sel_hi:[1,0]
	s_waitcnt vmcnt(2)
	v_pk_mul_f32 v[14:15], v[74:75], v[14:15]
	v_pk_mul_f32 v[12:13], v[72:73], v[12:13]
	v_pk_mul_f32 v[10:11], v[70:71], v[10:11]
	v_pk_mul_f32 v[8:9], v[68:69], v[8:9]
	v_pk_mul_f32 v[6:7], v[66:67], v[6:7]
	v_pk_mul_f32 v[4:5], v[64:65], v[4:5]
	v_pk_mul_f32 v[2:3], v[58:59], v[2:3]
	v_pk_mul_f32 v[0:1], v[56:57], v[0:1]
	s_and_b64 vcc, exec, s[4:5]
	s_cbranch_vccz .LBB0_475
	s_branch .LBB0_476
